# speedup vs baseline: 1.0072x; 1.0072x over previous
; __device__ __forceinline__ int otid(int wv) { return wv * 64 + olane(); }
; #define G_STAGE(bufoff, gbase, voff) do { _Pragma("unroll") for (int _i = 0; _i < 2; ++_i) \
;     __builtin_amdgcn_global_load_lds((const unsigned*)((const char*)(gbase) + (voff)[_i]), (LAS unsigned*)(lds + (bufoff) + ldsw + _i * 8192), 16, 0, 0); } while (0)
; #define WAIT_V(n) asm volatile("s_waitcnt vmcnt(" #n ")" ::: "memory")
; #define BAR __builtin_amdgcn_s_barrier()
; template <class Epi>
; __device__ __forceinline__ void gemm_phase(const bf16_t* __restrict__ A, int lda, const bf16_t* __restrict__ Bt, int ldb, int K, int nM, int nN, const Epi& epi, LAS unsigned char* lds, int wv) {
;     ...
;     const int tid = otid(wv), wid = wv, lane = tid & 63, wr = wid >> 2, wc = wid & 3, fr = lane & 15, fq = lane >> 4;
;     unsigned voffA[2];
; #pragma unroll
;     for (int i = 0; i < 2; ++i) { int R, C; stage_rc(tid * 16 + i * 8192, R, C); voffA[i] = (unsigned)(R * lda + C) * 2u; }
;     const size_t hstep = (size_t)128 * lda * 2, kstep = 128;
;     const unsigned ldsw = (unsigned)wid * 1024u;
;     const int aoff = lds_byte(wr * 64 + fr, fq * 8), boff = lds_byte(wc * 32 + fr, fq * 8);
;     const int nt = K / 64;
;     int pm, pn; tile_coords(bid, nM, nN, pm, pn);
;     const char* cA = (const char*)(A + (size_t)pm * 256 * lda);
;     const char* cB = (const char*)(Bt + (size_t)pn * 256 * ldb);
;     f32x4 acc[2][2][4][2];
; #pragma unroll
;     for (int a = 0; a < 2; ++a)
; #pragma unroll
;         for (int b = 0; b < 2; ++b)
; #pragma unroll
;             for (int m = 0; m < 4; ++m)
; #pragma unroll
;                 for (int n = 0; n < 2; ++n) acc[a][b][m][n] = (f32x4){0.f, 0.f, 0.f, 0.f};
;     bf16x8 At[4][2], B0[2][2], B1[2][2];
;     WAIT_V(0);
;     G_STAGE(G_SB(0, 0), cB, voffA); G_STAGE(G_SB(0, 1), cB + hstep, voffA); G_STAGE(G_SA(0, 0), cA, voffA); G_STAGE(G_SA(0, 1), cA + hstep, voffA);
;     if (wr == 1) BAR;
;     WAIT_V(2); BAR;
;     G_STAGE(G_SB(1, 0), cB + kstep, voffA); G_STAGE(G_SA(1, 0), cA + kstep, voffA); G_STAGE(G_SB(1, 1), cB + hstep + kstep, voffA);
;     WAIT_V(6); BAR;
.LBB0_43:
	v_lshl_add_u32 v0, v16, 4, s33
	v_ashrrev_i32_e32 v1, 31, v0
	v_lshrrev_b32_e32 v1, 22, v1
	v_add_u32_e32 v1, v0, v1
	v_ashrrev_i32_e32 v8, 10, v1
	v_mul_i32_i24_e32 v1, 0x400, v8
	v_sub_u32_e32 v1, v0, v1
	v_lshrrev_b32_e32 v2, 4, v1
	v_bitop3_b32 v1, v2, v1, 32 bitop3:0x6c
	v_ashrrev_i32_e32 v3, 31, v1
	v_lshrrev_b32_e32 v3, 26, v3
	v_add_u32_e32 v3, v1, v3
	v_lshlrev_b32_e32 v2, 3, v8
	v_ashrrev_i32_e32 v10, 6, v3
	v_lshlrev_b32_e32 v4, 5, v8
	v_and_b32_e32 v3, 0xc0, v3
	v_and_b32_e32 v2, 0xfffff0, v2
	v_and_b32_e32 v9, 32, v4
	v_sub_u32_e32 v1, v1, v3
	v_mov_b32_e32 v4, 1
	v_add_u32_e32 v2, v10, v2
	v_ashrrev_i16_sdwa v1, v4, sext(v1) dst_sel:DWORD dst_unused:UNUSED_PAD src0_sel:DWORD src1_sel:BYTE_0
	s_movk_i32 s9, 0xb00
	v_bfe_i32 v11, v1, 0, 16
	v_mul_lo_u32 v1, v2, s9
	v_or_b32_e32 v1, v1, v9
	v_add_u32_e32 v0, 0x2000, v0
	v_add_lshl_u32 v192, v1, v11, 1
	v_ashrrev_i32_e32 v1, 31, v0
	v_lshrrev_b32_e32 v1, 22, v1
	v_add_u32_e32 v1, v0, v1
	v_ashrrev_i32_e32 v12, 10, v1
	v_mul_i32_i24_e32 v1, 0x400, v12
	v_sub_u32_e32 v0, v0, v1
	v_lshrrev_b32_e32 v1, 4, v0
	v_bitop3_b32 v0, v1, v0, 32 bitop3:0x6c
	v_ashrrev_i32_e32 v2, 31, v0
	v_lshrrev_b32_e32 v2, 26, v2
	v_add_u32_e32 v2, v0, v2
	v_ashrrev_i32_e32 v14, 6, v2
	v_and_b32_e32 v2, 0xffc0, v2
	v_sub_u32_e32 v0, v0, v2
	v_lshrrev_b16_e32 v2, 7, v0
	s_add_i32 s7, s7, s8
	v_lshlrev_b32_e32 v1, 3, v12
	v_and_b32_e32 v2, 1, v2
	s_ashr_i32 s8, s7, 31
	v_and_b32_e32 v1, 0xfffff0, v1
	v_add_u16_e32 v0, v0, v2
	s_lshr_b32 s8, s8, 27
	v_add_u32_e32 v1, v14, v1
	v_ashrrev_i16_sdwa v0, v4, sext(v0) dst_sel:DWORD dst_unused:UNUSED_PAD src0_sel:DWORD src1_sel:BYTE_0
	s_add_i32 s8, s7, s8
	v_bfe_i32 v15, v0, 0, 16
	v_mul_lo_u32 v0, v1, s9
	s_ashr_i32 s9, s8, 5
	s_and_b32 s8, s8, 0xffe0
	s_sub_i32 s7, s7, s8
	s_bfe_i32 s8, s7, 0x80000
	s_bfe_u32 s8, s8, 0x3000c
	s_add_i32 s29, s7, s8
	s_bfe_i32 s8, s29, 0x80000
	s_and_b32 s29, s29, 0xf8
	s_sub_i32 s7, s7, s29
	s_lshl_b32 s9, s9, 3
	s_sext_i32_i16 s30, s8
	s_sext_i32_i8 s7, s7
	s_add_i32 s94, s9, s7
	s_xor_b32 s94, s94, 24
	s_ashr_i32 s7, s30, 3
	s_mul_hi_i32 s63, s7, 0xb0000
	s_mul_i32 s62, s7, 0xb0000
	s_lshr_b32 s8, s30, 3
	s_lshl_b64 s[30:31], s[62:63], 1
	s_add_u32 s54, s48, s30
	v_lshlrev_b32_e32 v3, 5, v12
	s_addc_u32 s55, s49, s31
	s_add_i32 s7, s33, 0
	v_and_b32_e32 v13, 32, v3
	s_waitcnt vmcnt(0)
	s_add_i32 m0, s7, 0x10000
	v_or_b32_e32 v0, v0, v13
	global_load_lds_dwordx4 v192, s[54:55]
	s_add_i32 m0, s7, 0x12000
	v_add_lshl_u32 v144, v0, v15, 1
	s_add_u32 s30, s54, 0xb0000
	global_load_lds_dwordx4 v144, s[54:55]
	s_addc_u32 s31, s55, 0
	s_add_i32 m0, s7, 0x14000
	s_mul_i32 s29, s94, 0x160000
	global_load_lds_dwordx4 v192, s[30:31]
	s_add_i32 m0, s7, 0x16000
	s_mul_hi_i32 s9, s94, 0x160000
	s_add_u32 s60, s20, s29
	s_addc_u32 s61, s21, s9
	s_add_i32 s29, s7, 0x2000
	global_load_lds_dwordx4 v144, s[30:31]
	s_mov_b32 m0, s7
	s_add_u32 s30, s60, 0xb0000
	global_load_lds_dwordx4 v192, s[60:61]
	s_mov_b32 m0, s29
	s_addc_u32 s31, s61, 0
	s_add_i32 s38, s7, 0x4000
	global_load_lds_dwordx4 v144, s[60:61]
	s_mov_b32 m0, s38
	s_add_i32 s39, s7, 0x6000
	global_load_lds_dwordx4 v192, s[30:31]
	s_mov_b32 m0, s39
	v_writelane_b32 v254, s82, 53
	global_load_lds_dwordx4 v144, s[30:31]
	v_readlane_b32 s30, v253, 8
	v_mov_b32_e32 v145, v193
	v_readlane_b32 s31, v253, 9
	v_writelane_b32 v254, s83, 54
	v_lshl_add_u64 v[6:7], s[54:55], 0, v[192:193]
	v_lshl_add_u64 v[4:5], s[54:55], 0, v[144:145]
	v_lshl_add_u64 v[0:1], s[60:61], 0, v[192:193]
	s_andn2_b64 vcc, exec, s[30:31]
	v_lshl_add_u64 v[2:3], s[60:61], 0, v[144:145]
	s_cbranch_vccnz .LBB0_45
	s_barrier

; template <class Epi>
; __device__ __forceinline__ void gemm_phase(const bf16_t* __restrict__ A, int lda, const bf16_t* __restrict__ Bt, int ldb, int K, int nM, int nN, const Epi& epi, LAS unsigned char* lds, int wv) {
;     ...
;         const int L = (i + 1) * G + bid;
;         const bool has_next = L < nwg;
;         int npm = pm, npn = pn; if (has_next) tile_coords(L, nM, nN, npm, npn);
.LBB0_52:
	s_ashr_i32 s8, s30, 3
	s_add_i32 s8, s40, s8
	s_ashr_i32 s9, s8, 31
	s_lshr_b32 s9, s9, 27
	s_add_i32 s9, s8, s9
	s_ashr_i32 s30, s9, 5
	s_and_b32 s9, s9, 0xffe0
	s_sub_i32 s8, s8, s9
	s_bfe_i32 s9, s8, 0x80000
	s_bfe_u32 s9, s9, 0x3000c
	s_add_i32 s9, s8, s9
	s_bfe_i32 s31, s9, 0x80000
	s_and_b32 s9, s9, 0xf8
	s_sub_i32 s8, s8, s9
	s_lshl_b32 s30, s30, 3
	s_sext_i32_i16 s31, s31
	s_sext_i32_i8 s8, s8
	s_add_i32 s83, s30, s8
	s_xor_b32 s83, s83, 24
	s_ashr_i32 s82, s31, 3
